# stack + ctx_gemm<3> units moved to CUs 64..127 (CUs 0..31 already carry the context attention units)
# baseline (speedup 1.0000x reference)
.LBB1_482:
	s_andn2_b64 vcc, exec, s[36:37]
	s_waitcnt vmcnt(0) lgkmcnt(0)
	s_barrier
	s_cbranch_vccnz .LBB1_487
	s_add_i32 s1, s90, 0xc0
	s_and_b32 s1, s1, 0xff
	s_mov_b32 s5, s91
	s_mov_b32 s6, -1
	v_readlane_b32 s30, v254, 46
	v_mbcnt_lo_u32_b32 v0, s6, 0
	v_mbcnt_hi_u32_b32 v0, s6, v0
	v_readlane_b32 s36, v254, 48
	v_lshl_add_u32 v2, s5, 6, v0
	s_cmp_gt_i32 s1, 63
	v_readlane_b32 s31, v254, 47
	v_readlane_b32 s37, v254, 49
	s_mov_b64 s[38:39], 0x200
	s_mov_b64 s[40:41], 0x1000
	s_mov_b64 s[42:43], 0x1100
	s_mov_b64 s[56:57], 0x1200
	s_mov_b64 s[58:59], 0x1300
	s_mov_b64 s[60:61], 0x100
	s_mov_b64 s[62:63], 0x300
	v_readlane_b32 s6, v254, 31
	v_readlane_b32 s7, v254, 32
	s_cbranch_scc1 .LBB1_486
	v_bfe_u32 v7, v2, 4, 2
	s_lshl_b32 s7, s5, 3
	s_mov_b32 s68, s6
	s_lshl_b32 s6, s5, 1
	v_or_b32_e32 v0, s7, v7
	v_and_b32_e32 v3, 15, v2
	s_and_b32 s6, s6, 2
	v_lshrrev_b32_e32 v5, 4, v2
	v_bitop3_b32 v4, v7, v2, s7 bitop3:0x36
	v_bitop3_b32 v6, v0, v2, 4 bitop3:0x36
	v_bfi_b32 v2, 15, v2, s7
	s_lshl_b32 s9, s5, 11
	s_and_b32 s5, s7, -16
	v_lshlrev_b32_e32 v2, 8, v2
	s_lshl_b32 s7, s6, 12
	s_add_i32 s10, 0, 0x18000
	v_lshlrev_b32_e32 v16, 8, v3
	s_add_i32 s11, s10, s7
	v_bitop3_b32 v5, v5, v3, 3 bitop3:0x6c
	v_add_u32_e32 v15, s10, v2
	s_add_i32 s10, 0, 0x10000
	v_lshlrev_b32_e32 v4, 3, v4
	v_lshlrev_b32_e32 v6, 3, v6
	v_add_u32_e32 v8, s11, v16
	v_lshlrev_b32_e32 v10, 4, v5
	s_add_i32 s11, s7, 0
	v_bitop3_b32 v5, v7, v3, 4 bitop3:0x36
	s_add_i32 s7, s10, s7
	v_and_b32_e32 v4, 0x78, v4
	v_and_b32_e32 v6, 0x78, v6
	s_addk_i32 s5, 0x2000
	s_lshl_b32 s6, s6, 4
	v_bitop3_b32 v9, v7, v3, 12 bitop3:0x36
	v_add_u32_e32 v12, s11, v16
	v_lshlrev_b32_e32 v13, 4, v5
	v_bitop3_b32 v5, v7, v3, 8 bitop3:0x36
	v_add_u32_e32 v16, s7, v16
	s_add_i32 s7, s9, 0
	v_ashrrev_i32_e32 v1, 31, v0
	v_lshlrev_b32_e32 v9, 4, v9
	v_add_u32_e32 v11, 0, v2
	v_lshlrev_b32_e32 v14, 4, v5
	v_add_u32_e32 v17, s10, v2
	v_or_b32_e32 v18, s5, v3
	v_lshl_or_b32 v19, v7, 2, s6
	s_lshl_b32 s5, s1, 3
	s_lshl_b32 s6, s1, 6
	v_lshlrev_b32_e32 v112, 1, v4
	v_lshlrev_b32_e32 v2, 1, v6
	s_add_i32 s9, s7, 0x4400
	s_add_i32 s10, s7, 0x8400
	s_add_i32 s11, s7, 0xc400
	s_add_i32 s24, s7, 0x10400
	s_add_i32 s25, s7, 0x14400
	s_add_i32 s26, s7, 0x18400
	s_add_i32 s27, s7, 0x1c400
